# attention: drop redundant hazard nops and per-tile register copies in the softmax/QK stream, prefetch all V fragments before the PV MFMAs
# speedup vs baseline: 1.0488x; 1.0111x over previous
; __device__ __forceinline__ void attn_unit(const Params& P, unsigned char* lds, int h, int qb) {
;     ...
;         } else if (act) {
;             ATT_GAP(0, 32);
;         }
;         if (act) {
;             lsum += ps0 + ps1;
.LBB0_879:
	s_mov_b64 s[10:11], 0
	s_and_b64 vcc, exec, s[8:9]
	s_mov_b64 s[12:13], 0
	s_cbranch_vccz .LBB0_881
	v_mov_b32_e32 v2, v128
	v_mov_b32_e32 v4, v117
	v_exp_f32_e32 v11, v2
	v_mov_b32_e32 v2, v129
	s_mov_b64 s[12:13], -1
	v_exp_f32_e32 v223, v2
	v_mov_b32_e32 v2, v130
	v_exp_f32_e32 v219, v2
	v_mov_b32_e32 v2, v131
	v_exp_f32_e32 v225, v2
	v_mov_b32_e32 v2, v132
	v_exp_f32_e32 v13, v2
	v_mov_b32_e32 v2, v133
	v_exp_f32_e32 v15, v2
	v_mov_b32_e32 v2, v134
	v_exp_f32_e32 v181, v2
	v_mov_b32_e32 v2, v135
	v_exp_f32_e32 v183, v2
	v_mov_b32_e32 v2, v136
	v_exp_f32_e32 v209, v2
	v_mov_b32_e32 v2, v137
	v_cvt_pk_bf16_f32 v5, v181, v183
	v_exp_f32_e32 v211, v2
	v_mov_b32_e32 v2, v138
	v_exp_f32_e32 v213, v2
	v_mov_b32_e32 v2, v139
	v_cvt_pk_bf16_f32 v6, v209, v211
	v_exp_f32_e32 v215, v2
	v_mov_b32_e32 v2, v140
	v_exp_f32_e32 v217, v2
	v_mov_b32_e32 v2, v141
	v_cvt_pk_bf16_f32 v7, v213, v215
	v_exp_f32_e32 v221, v2
	v_mov_b32_e32 v2, v142
	v_exp_f32_e32 v227, v2
	v_mov_b32_e32 v2, v143
	v_cvt_pk_bf16_f32 v8, v217, v221
	v_exp_f32_e32 v229, v2
	v_mov_b32_e32 v2, v112
	v_exp_f32_e32 v10, v2
	v_mov_b32_e32 v2, v113
	v_cvt_pk_bf16_f32 v9, v227, v229
	v_exp_f32_e32 v222, v2
	v_mov_b32_e32 v2, v114
	v_exp_f32_e32 v218, v2
	v_mov_b32_e32 v2, v115
	v_exp_f32_e32 v224, v2
	v_mov_b32_e32 v2, v116
	v_exp_f32_e32 v12, v2
	v_pk_add_f32 v[2:3], v[10:11], 0 op_sel_hi:[1,0]
	v_exp_f32_e32 v14, v4
	v_mov_b32_e32 v4, v118
	v_pk_add_f32 v[2:3], v[2:3], v[222:223]
	v_exp_f32_e32 v180, v4
	v_mov_b32_e32 v4, v119
	v_pk_add_f32 v[2:3], v[2:3], v[218:219]
	v_exp_f32_e32 v182, v4
	v_mov_b32_e32 v4, v120
	v_pk_add_f32 v[2:3], v[2:3], v[224:225]
	v_exp_f32_e32 v208, v4
	v_mov_b32_e32 v4, v121
	v_pk_add_f32 v[2:3], v[2:3], v[12:13]
	v_exp_f32_e32 v210, v4
	v_mov_b32_e32 v4, v122
	v_pk_add_f32 v[2:3], v[2:3], v[14:15]
	v_exp_f32_e32 v212, v4
	v_mov_b32_e32 v4, v123
	v_pk_add_f32 v[2:3], v[2:3], v[180:181]
	v_exp_f32_e32 v214, v4
	v_mov_b32_e32 v4, v124
	v_pk_add_f32 v[2:3], v[2:3], v[182:183]
	v_cvt_pk_bf16_f32 v10, v10, v222
	v_pk_add_f32 v[2:3], v[2:3], v[208:209]
	v_exp_f32_e32 v216, v4
	v_mov_b32_e32 v4, v125
	v_pk_add_f32 v[2:3], v[2:3], v[210:211]
	v_cvt_pk_bf16_f32 v12, v12, v14
	v_pk_add_f32 v[2:3], v[2:3], v[212:213]
	v_exp_f32_e32 v220, v4
	v_mov_b32_e32 v4, v126
	v_pk_add_f32 v[2:3], v[2:3], v[214:215]
	v_cvt_pk_bf16_f32 v181, v212, v214
	v_pk_add_f32 v[2:3], v[2:3], v[216:217]
	v_exp_f32_e32 v226, v4
	v_pk_add_f32 v[2:3], v[2:3], v[220:221]
	v_mov_b32_e32 v4, v127
	v_pk_add_f32 v[2:3], v[2:3], v[226:227]
	v_exp_f32_e32 v228, v4
	v_cvt_pk_bf16_f32 v4, v13, v15
	v_pk_add_f32 v[230:231], v[2:3], v[228:229]
	v_cvt_pk_bf16_f32 v2, v11, v223
	v_cvt_pk_bf16_f32 v3, v219, v225
	v_cvt_pk_bf16_f32 v11, v218, v224
	v_cvt_pk_bf16_f32 v13, v180, v182
	v_cvt_pk_bf16_f32 v180, v208, v210
	v_cvt_pk_bf16_f32 v182, v216, v220
	v_cvt_pk_bf16_f32 v183, v226, v228
	s_add_i32 s25, s21, 1
	s_and_b64 vcc, exec, s[10:11]
	s_cbranch_vccz .LBB0_893
	s_branch .LBB0_882

; __device__ __forceinline__ int crow(int r, int hi) { return (r & 3) + 8 * (r >> 2) + 4 * hi; }
; #define SBAR() __builtin_amdgcn_sched_barrier(0)
; __device__ __forceinline__ void attn_mask(f32x16& s0, f32x16& s1, int k0, int qg, int hi) {
; #pragma unroll
;     for (int r = 0; r < 16; ++r) { const int key = k0 + crow(r, hi); if (key > qg) s0[r] = -1e30f; if (key + 32 > qg) s1[r] = -1e30f; }
; }
; __device__ __forceinline__ void attn_unit(const Params& P, unsigned char* lds, int h, int qb) {
;     ...
;         if (act && actn) {
;             const unsigned char* Kn = lds + ((t + 1) & 1) * KBUF + r32 * KROW + hi * 16;
;             SBAR();
; #pragma unroll
;             for (int g = 0; g < 6; ++g) {
;                 const bf16x8 ka = *(const bf16x8*)(Kn + g * 32), kb = *(const bf16x8*)(Kn + 32 * KROW + g * 32);
;                 n0 = __builtin_amdgcn_mfma_f32_32x32x16_bf16(ka, qr[g], g == 0 ? negm : n0, 0, 0, 0);
;                 SBAR();
;                 ATT_GAP((32 * (2 * g)) / 12, (32 * (2 * g + 1)) / 12);
;                 SBAR();
;                 n1 = __builtin_amdgcn_mfma_f32_32x32x16_bf16(kb, qr[g], g == 0 ? negm : n1, 0, 0, 0);
;                 SBAR();
;                 ATT_GAP((32 * (2 * g + 1)) / 12, (32 * (2 * g + 2)) / 12);
;                 SBAR();
;             }
;             if ((t + 1) * 64 + 63 > qw0) attn_mask(n0, n1, (t + 1) * 64, qg, hi);
.LBB0_882:
	s_bitcmp1_b32 s25, 0
	s_cselect_b32 s10, 0x3400, 0
	v_add_u32_e32 v208, s10, v248
	ds_read_b128 v[2:5], v208
	ds_read_b128 v[6:9], v208 offset:6656
	s_waitcnt lgkmcnt(1)
	v_mfma_f32_32x32x16_bf16 v[16:31], v[2:5], v[160:163], v[64:79]
	v_exp_f32_e32 v15, v128
	v_exp_f32_e32 v97, v129
	s_nop 0
	v_cvt_pk_bf16_f32 v2, v15, v97
	s_waitcnt lgkmcnt(0)
	v_mfma_f32_32x32x16_bf16 v[80:95], v[6:9], v[160:163], v[64:79]
	v_exp_f32_e32 v99, v130
	v_exp_f32_e32 v101, v131
	v_exp_f32_e32 v103, v132
	v_cvt_pk_bf16_f32 v3, v99, v101
	ds_read_b128 v[4:7], v208 offset:32
	ds_read_b128 v[8:11], v208 offset:6688
	s_waitcnt lgkmcnt(1)
	v_mfma_f32_32x32x16_bf16 v[16:31], v[4:7], v[144:147], v[16:31]
	v_exp_f32_e32 v105, v133
	v_exp_f32_e32 v107, v134
	v_cvt_pk_bf16_f32 v4, v103, v105
	v_exp_f32_e32 v109, v135
	s_nop 0
	v_cvt_pk_bf16_f32 v5, v107, v109
	s_waitcnt lgkmcnt(0)
	v_mfma_f32_32x32x16_bf16 v[80:95], v[8:11], v[144:147], v[80:95]
	v_exp_f32_e32 v111, v136
	v_exp_f32_e32 v129, v137
	s_nop 0
	v_cvt_pk_bf16_f32 v6, v111, v129
	ds_read_b128 v[8:11], v208 offset:64
	ds_read_b128 v[180:183], v208 offset:6720
	s_waitcnt lgkmcnt(1)
	v_mfma_f32_32x32x16_bf16 v[16:31], v[8:11], v[148:151], v[16:31]
	v_exp_f32_e32 v131, v138
	v_exp_f32_e32 v133, v139
	v_exp_f32_e32 v135, v140
	v_cvt_pk_bf16_f32 v7, v131, v133
	s_waitcnt lgkmcnt(0)
	v_mfma_f32_32x32x16_bf16 v[80:95], v[180:183], v[148:151], v[80:95]
	v_exp_f32_e32 v137, v141
	v_exp_f32_e32 v139, v142
	v_cvt_pk_bf16_f32 v8, v135, v137
	v_exp_f32_e32 v141, v143
	s_nop 0
	v_cvt_pk_bf16_f32 v9, v139, v141
	ds_read_b128 v[10:13], v208 offset:96
	ds_read_b128 v[180:183], v208 offset:6752
	s_waitcnt lgkmcnt(1)
	v_mfma_f32_32x32x16_bf16 v[16:31], v[10:13], v[152:155], v[16:31]
	v_exp_f32_e32 v14, v112
	v_exp_f32_e32 v96, v113
	s_nop 0
	v_cvt_pk_bf16_f32 v10, v14, v96
	s_waitcnt lgkmcnt(0)
	v_mfma_f32_32x32x16_bf16 v[80:95], v[180:183], v[152:155], v[80:95]
	v_exp_f32_e32 v98, v114
	v_exp_f32_e32 v100, v115
	v_exp_f32_e32 v102, v116
	v_cvt_pk_bf16_f32 v11, v98, v100
	ds_read_b128 v[112:115], v208 offset:128
	ds_read_b128 v[180:183], v208 offset:6784
	s_waitcnt lgkmcnt(1)
	v_mfma_f32_32x32x16_bf16 v[16:31], v[112:115], v[156:159], v[16:31]
	v_exp_f32_e32 v104, v117
	v_exp_f32_e32 v106, v118
	v_cvt_pk_bf16_f32 v12, v102, v104
	v_exp_f32_e32 v108, v119
	s_nop 0
	v_cvt_pk_bf16_f32 v13, v106, v108
	s_waitcnt lgkmcnt(0)
	v_mfma_f32_32x32x16_bf16 v[80:95], v[180:183], v[156:159], v[80:95]
	v_exp_f32_e32 v110, v120
	v_exp_f32_e32 v128, v121
	s_nop 0
	v_cvt_pk_bf16_f32 v180, v110, v128
	ds_read_b128 v[112:115], v208 offset:160
	ds_read_b128 v[116:119], v208 offset:6816
	s_waitcnt lgkmcnt(1)
	v_mfma_f32_32x32x16_bf16 v[16:31], v[112:115], v[164:167], v[16:31]
	v_exp_f32_e32 v130, v122
	v_exp_f32_e32 v132, v123
	v_exp_f32_e32 v134, v124
	v_cvt_pk_bf16_f32 v181, v130, v132
	s_waitcnt lgkmcnt(0)
	v_mfma_f32_32x32x16_bf16 v[80:95], v[116:119], v[164:167], v[80:95]
	v_exp_f32_e32 v136, v125
	v_exp_f32_e32 v138, v126
	v_cvt_pk_bf16_f32 v182, v134, v136
	v_exp_f32_e32 v140, v127
	s_nop 0
	v_cvt_pk_bf16_f32 v183, v138, v140
	s_cmp_le_i32 s20, s15
	s_cbranch_scc1 .LBB0_884
	v_add_u32_e32 v112, s20, v249
	v_subrev_u32_e32 v114, 31, v112
	v_subrev_u32_e32 v113, 63, v112
	v_cmp_le_i32_e32 vcc, v114, v198
	s_nop 1
	v_cndmask_b32_e32 v80, v244, v80, vcc
	v_cmp_lt_i32_e32 vcc, v113, v198
	s_nop 1
	v_cndmask_b32_e32 v17, v244, v17, vcc
	v_cmp_le_i32_e32 vcc, v113, v198
	v_subrev_u32_e32 v113, 30, v112
	s_nop 0
	v_cndmask_b32_e32 v16, v244, v16, vcc
	v_cmp_le_i32_e32 vcc, v113, v198
	v_subrev_u32_e32 v113, 61, v112
	s_nop 0
	v_cndmask_b32_e32 v81, v244, v81, vcc
	v_cmp_le_i32_e32 vcc, v113, v198
	v_subrev_u32_e32 v113, 29, v112
	s_nop 0
	v_cndmask_b32_e32 v18, v244, v18, vcc
	v_cmp_le_i32_e32 vcc, v113, v198
	v_subrev_u32_e32 v113, 60, v112
	s_nop 0
	v_cndmask_b32_e32 v82, v244, v82, vcc
	v_cmp_le_i32_e32 vcc, v113, v198
	v_subrev_u32_e32 v113, 28, v112
	s_nop 0
	v_cndmask_b32_e32 v19, v244, v19, vcc
	v_cmp_le_i32_e32 vcc, v113, v198
	v_subrev_u32_e32 v113, 55, v112
	s_nop 0
	v_cndmask_b32_e32 v83, v244, v83, vcc
	v_cmp_le_i32_e32 vcc, v113, v198
	v_subrev_u32_e32 v113, 23, v112
	s_nop 0
	v_cndmask_b32_e32 v20, v244, v20, vcc
	v_cmp_le_i32_e32 vcc, v113, v198
	v_subrev_u32_e32 v113, 54, v112
	s_nop 0
	v_cndmask_b32_e32 v84, v244, v84, vcc
	v_cmp_le_i32_e32 vcc, v113, v198
	v_subrev_u32_e32 v113, 22, v112
	s_nop 0
	v_cndmask_b32_e32 v21, v244, v21, vcc
	v_cmp_le_i32_e32 vcc, v113, v198
	v_subrev_u32_e32 v113, 53, v112
	s_nop 0
	v_cndmask_b32_e32 v85, v244, v85, vcc
	v_cmp_le_i32_e32 vcc, v113, v198
	v_subrev_u32_e32 v113, 21, v112
	s_nop 0
	v_cndmask_b32_e32 v22, v244, v22, vcc
	v_cmp_le_i32_e32 vcc, v113, v198
	v_subrev_u32_e32 v113, 52, v112
	s_nop 0
	v_cndmask_b32_e32 v86, v244, v86, vcc
	v_cmp_le_i32_e32 vcc, v113, v198
	v_subrev_u32_e32 v113, 20, v112
	s_nop 0
	v_cndmask_b32_e32 v23, v244, v23, vcc
	v_cmp_le_i32_e32 vcc, v113, v198
	v_subrev_u32_e32 v113, 47, v112
	s_nop 0
	v_cndmask_b32_e32 v87, v244, v87, vcc
	v_cmp_le_i32_e32 vcc, v113, v198
	v_add_u32_e32 v113, -15, v112
	s_nop 0
	v_cndmask_b32_e32 v24, v244, v24, vcc
	v_cmp_le_i32_e32 vcc, v113, v198
	v_subrev_u32_e32 v113, 46, v112
	s_nop 0
	v_cndmask_b32_e32 v88, v244, v88, vcc
	v_cmp_le_i32_e32 vcc, v113, v198
	v_add_u32_e32 v113, -14, v112
	s_nop 0
	v_cndmask_b32_e32 v25, v244, v25, vcc
	v_cmp_le_i32_e32 vcc, v113, v198
	v_subrev_u32_e32 v113, 45, v112
	s_nop 0
	v_cndmask_b32_e32 v89, v244, v89, vcc
	v_cmp_le_i32_e32 vcc, v113, v198
	v_add_u32_e32 v113, -13, v112
	s_nop 0
	v_cndmask_b32_e32 v26, v244, v26, vcc
	v_cmp_le_i32_e32 vcc, v113, v198
	v_subrev_u32_e32 v113, 44, v112
	s_nop 0
	v_cndmask_b32_e32 v90, v244, v90, vcc
	v_cmp_le_i32_e32 vcc, v113, v198
	v_add_u32_e32 v113, -12, v112
	s_nop 0
	v_cndmask_b32_e32 v27, v244, v27, vcc
	v_cmp_le_i32_e32 vcc, v113, v198
	v_subrev_u32_e32 v113, 39, v112
	s_nop 0
	v_cndmask_b32_e32 v91, v244, v91, vcc
	v_cmp_le_i32_e32 vcc, v113, v198
	v_add_u32_e32 v113, -7, v112
	s_nop 0
	v_cndmask_b32_e32 v28, v244, v28, vcc
	v_cmp_le_i32_e32 vcc, v113, v198
	v_subrev_u32_e32 v113, 38, v112
	s_nop 0
	v_cndmask_b32_e32 v92, v244, v92, vcc
	v_cmp_le_i32_e32 vcc, v113, v198
	v_add_u32_e32 v113, -6, v112
	s_nop 0
	v_cndmask_b32_e32 v29, v244, v29, vcc
	v_cmp_le_i32_e32 vcc, v113, v198
	v_subrev_u32_e32 v113, 37, v112
	s_nop 0
	v_cndmask_b32_e32 v93, v244, v93, vcc
	v_cmp_le_i32_e32 vcc, v113, v198
	v_add_u32_e32 v113, -5, v112
	s_nop 0
	v_cndmask_b32_e32 v30, v244, v30, vcc
	v_cmp_le_i32_e32 vcc, v113, v198
	v_subrev_u32_e32 v113, 36, v112
	v_add_u32_e32 v112, -4, v112
	v_cndmask_b32_e32 v94, v244, v94, vcc
	v_cmp_le_i32_e32 vcc, v113, v198
	s_nop 1
	v_cndmask_b32_e32 v31, v244, v31, vcc
	v_cmp_le_i32_e32 vcc, v112, v198
	s_nop 1
	v_cndmask_b32_e32 v95, v244, v95, vcc
; __device__ __forceinline__ void attn_unit(const Params& P, unsigned char* lds, int h, int qb) {
;     ...
;             lsum += ps0 + ps1;
.LBB0_884:
	v_pk_add_f32 v[14:15], v[14:15], 0 op_sel_hi:[1,0]
	s_nop 0
	v_pk_add_f32 v[14:15], v[14:15], v[96:97]
	v_pk_add_f32 v[14:15], v[14:15], v[98:99]
	v_pk_add_f32 v[14:15], v[14:15], v[100:101]
	v_pk_add_f32 v[14:15], v[14:15], v[102:103]
	v_pk_add_f32 v[14:15], v[14:15], v[104:105]
	v_pk_add_f32 v[14:15], v[14:15], v[106:107]
	v_pk_add_f32 v[14:15], v[14:15], v[108:109]
	v_pk_add_f32 v[14:15], v[14:15], v[110:111]
	v_pk_add_f32 v[14:15], v[14:15], v[128:129]
	v_pk_add_f32 v[14:15], v[14:15], v[130:131]
	v_pk_add_f32 v[14:15], v[14:15], v[132:133]
	v_pk_add_f32 v[14:15], v[14:15], v[134:135]
	v_pk_add_f32 v[14:15], v[14:15], v[136:137]
	v_pk_add_f32 v[14:15], v[14:15], v[138:139]
	v_pk_add_f32 v[230:231], v[14:15], v[140:141]
	s_branch .LBB0_894

; __device__ __forceinline__ void attn_unit(const Params& P, unsigned char* lds, int h, int qb) {
;     ...
;             if (t == 0 || __any(mx > THR)) {
;                 const float dl = (t == 0) ? mx : fmaxf(mx, 0.f), f = __builtin_amdgcn_exp2f(-dl);
;                 m += dl; lsum *= f;
; #pragma unroll
;                 for (int r = 0; r < 16; ++r) { c0[r] -= dl; c1[r] -= dl; o0[r] *= f; o1[r] *= f; negm[r] = -m; }
;             }
;         }
;     ...
;         c0 = n0; c1 = n1;
.LBB0_890:
.LBB0_891:
	v_mov_b64_e32 v[142:143], v[30:31]
	v_mov_b64_e32 v[126:127], v[94:95]
	v_mov_b64_e32 v[140:141], v[28:29]
	v_mov_b64_e32 v[138:139], v[26:27]
	v_mov_b64_e32 v[136:137], v[24:25]
	v_mov_b64_e32 v[134:135], v[22:23]
	v_mov_b64_e32 v[132:133], v[20:21]
	v_mov_b64_e32 v[130:131], v[18:19]
	v_mov_b64_e32 v[128:129], v[16:17]
	v_mov_b64_e32 v[124:125], v[92:93]
	v_mov_b64_e32 v[122:123], v[90:91]
	v_mov_b64_e32 v[120:121], v[88:89]
	v_mov_b64_e32 v[118:119], v[86:87]
	v_mov_b64_e32 v[116:117], v[84:85]
	v_mov_b64_e32 v[114:115], v[82:83]
	v_mov_b64_e32 v[112:113], v[80:81]
	s_cmp_ge_i32 s21, s18
	s_cbranch_scc1 .LBB0_879

; __device__ __forceinline__ void attn_unit(const Params& P, unsigned char* lds, int h, int qb) {
;     ...
;         if (act) {
;             lsum += ps0 + ps1;
;             const unsigned char* Vb = lds + 2 * KBUF + (t & 1) * VBUF;
; #pragma unroll
;             for (int ks = 0; ks < 4; ++ks) {
;                 const bf16x8 pa = __builtin_bit_cast(bf16x8, pw[ks]);
;                 const unsigned char* va = Vb + r32 * VROW + (16 * ks + 4 * hi) * 2;
;                 const v2u l0 = *(const v2u*)va, h0 = *(const v2u*)(va + 16);
;                 const v2u l1 = *(const v2u*)(va + 32 * VROW), h1 = *(const v2u*)(va + 32 * VROW + 16);
;                 const bf16x8 vf0 = __builtin_bit_cast(bf16x8, ((v4u){l0.x, l0.y, h0.x, h0.y}));
;                 const bf16x8 vf1 = __builtin_bit_cast(bf16x8, ((v4u){l1.x, l1.y, h1.x, h1.y}));
;                 o0 = __builtin_amdgcn_mfma_f32_32x32x16_bf16(vf0, pa, o0, 0, 0, 0);
;                 o1 = __builtin_amdgcn_mfma_f32_32x32x16_bf16(vf1, pa, o1, 0, 0, 0);
;             }
;         }
.LBB0_894:
	s_andn2_b64 vcc, exec, s[8:9]
	s_cbranch_vccnz .LBB0_896
	s_bitcmp1_b32 s21, 0
	s_cselect_b32 s8, 0x2200, 0
	v_add_u32_e32 v14, s8, v250
	v_add_u32_e32 v15, 0x6800, v14
	v_add_u32_e32 v14, 0x7800, v14
	ds_read2_b64 v[112:115], v15 offset1:2
	ds_read2_b64 v[116:119], v14 offset0:32 offset1:34
	ds_read2_b64 v[120:123], v15 offset0:4 offset1:6
	ds_read2_b64 v[124:127], v14 offset0:36 offset1:38
	ds_read2_b64 v[128:131], v15 offset0:8 offset1:10
	ds_read2_b64 v[132:135], v14 offset0:40 offset1:42
	ds_read2_b64 v[136:139], v15 offset0:12 offset1:14
	ds_read2_b64 v[140:143], v14 offset0:44 offset1:46
	v_add_f32_e32 v96, v230, v231
	v_add_f32_e32 v236, v236, v96
	s_waitcnt lgkmcnt(7)
	v_mfma_f32_32x32x16_bf16 v[48:63], v[112:115], v[2:5], v[48:63]
	s_waitcnt lgkmcnt(6)
	v_mfma_f32_32x32x16_bf16 v[32:47], v[116:119], v[2:5], v[32:47]
	s_waitcnt lgkmcnt(5)
	v_mfma_f32_32x32x16_bf16 v[48:63], v[120:123], v[6:9], v[48:63]
	s_waitcnt lgkmcnt(4)
	v_mfma_f32_32x32x16_bf16 v[32:47], v[124:127], v[6:9], v[32:47]
	s_waitcnt lgkmcnt(3)
	v_mfma_f32_32x32x16_bf16 v[48:63], v[128:131], v[10:13], v[48:63]
	s_waitcnt lgkmcnt(2)
	v_mfma_f32_32x32x16_bf16 v[32:47], v[132:135], v[10:13], v[32:47]
	s_waitcnt lgkmcnt(1)
	v_mfma_f32_32x32x16_bf16 v[48:63], v[136:139], v[180:183], v[48:63]
	s_waitcnt lgkmcnt(0)
	v_mfma_f32_32x32x16_bf16 v[32:47], v[140:143], v[180:183], v[32:47]
